# stack7 + up epilogue store tail: seven of the eight row addresses formed as first address + K*stride (scalar product, one 64-bit add) instead of a 64-bit multiply-add each
# speedup vs baseline: 1.0131x; 1.0089x over previous
.LBB0_738:
	s_or_b64 exec, exec, s[0:1]
	s_mov_b32 s0, 0
	v_pk_fma_f32 v[46:47], v[142:143], v[186:187], v[146:147]
	v_pk_fma_f32 v[48:49], v[182:183], v[162:163], v[166:167]
	v_pk_fma_f32 v[198:199], v[184:185], v[164:165], v[168:169]
	v_pk_fma_f32 v[46:47], v[126:127], v[170:171], v[46:47]
	v_pk_fma_f32 v[48:49], v[114:115], v[178:179], v[48:49]
	v_pk_fma_f32 v[198:199], v[116:117], v[180:181], v[198:199]
	v_pk_fma_f32 v[46:47], v[122:123], v[158:159], v[46:47]
	v_pk_fma_f32 v[48:49], v[110:111], v[194:195], v[48:49]
	v_pk_fma_f32 v[200:201], v[170:171], v[142:143], v[146:147]
	v_pk_mul_f32 v[202:203], v[46:47], s[82:83] op_sel_hi:[1,0]
	v_pk_fma_f32 v[198:199], v[112:113], v[196:197], v[198:199]
	v_pk_fma_f32 v[200:201], v[126:127], v[158:159], v[200:201]
	v_exp_f32_e32 v204, v202
	v_exp_f32_e32 v205, v203
	v_pk_fma_f32 v[200:201], v[122:123], v[154:155], v[200:201]
	v_pk_fma_f32 v[202:203], v[180:181], v[164:165], v[168:169]
	v_pk_fma_f32 v[206:207], v[178:179], v[162:163], v[166:167]
	v_pk_add_f32 v[204:205], v[204:205], 1.0 op_sel_hi:[1,0]
	v_pk_fma_f32 v[202:203], v[196:197], v[116:117], v[202:203]
	v_pk_fma_f32 v[206:207], v[194:195], v[114:115], v[206:207]
	v_pk_fma_f32 v[196:197], v[196:197], v[164:165], v[168:169]
	v_pk_fma_f32 v[202:203], v[112:113], v[192:193], v[202:203]
	v_pk_fma_f32 v[206:207], v[110:111], v[190:191], v[206:207]
	v_pk_fma_f32 v[158:159], v[158:159], v[142:143], v[146:147]
	v_pk_fma_f32 v[194:195], v[194:195], v[162:163], v[166:167]
	v_pk_fma_f32 v[158:159], v[154:155], v[126:127], v[158:159]
	v_pk_fma_f32 v[154:155], v[154:155], v[142:143], v[146:147]
	v_pk_fma_f32 v[196:197], v[192:193], v[116:117], v[196:197]
	v_fmac_f32_dpp v158, v186, v122 row_shr:1 row_mask:0xf bank_mask:0xf bound_ctrl:1
	v_fmac_f32_dpp v159, v187, v123 row_shr:1 row_mask:0xf bank_mask:0xf bound_ctrl:1
	v_fmac_f32_dpp v154, v186, v126 row_shr:1 row_mask:0xf bank_mask:0xf bound_ctrl:1
	v_fmac_f32_dpp v155, v187, v127 row_shr:1 row_mask:0xf bank_mask:0xf bound_ctrl:1
	v_rcp_f32_e32 v186, v204
	v_rcp_f32_e32 v187, v205
	v_pk_mul_f32 v[204:205], v[200:201], s[82:83] op_sel_hi:[1,0]
	v_fmac_f32_dpp v154, v170, v122 row_shr:1 row_mask:0xf bank_mask:0xf bound_ctrl:1
	v_fmac_f32_dpp v155, v171, v123 row_shr:1 row_mask:0xf bank_mask:0xf bound_ctrl:1
	v_pk_fma_f32 v[170:171], v[190:191], v[114:115], v[194:195]
	v_pk_mul_f32 v[46:47], v[46:47], v[186:187]
	v_exp_f32_e32 v186, v204
	v_exp_f32_e32 v187, v205
	v_pk_mul_f32 v[46:47], v[48:49], v[46:47]
	v_pk_mul_f32 v[48:49], v[154:155], s[82:83] op_sel_hi:[1,0]
	v_pk_fma_f32 v[190:191], v[190:191], v[162:163], v[166:167]
	v_pk_add_f32 v[186:187], v[186:187], 1.0 op_sel_hi:[1,0]
	v_exp_f32_e32 v194, v48
	v_exp_f32_e32 v195, v49
	v_rcp_f32_e32 v48, v186
	v_rcp_f32_e32 v49, v187
	v_fmac_f32_dpp v190, v182, v114 row_shr:1 row_mask:0xf bank_mask:0xf bound_ctrl:1
	v_fmac_f32_dpp v191, v183, v115 row_shr:1 row_mask:0xf bank_mask:0xf bound_ctrl:1
	v_pk_add_f32 v[186:187], v[194:195], 1.0 op_sel_hi:[1,0]
	v_fmac_f32_dpp v190, v178, v110 row_shr:1 row_mask:0xf bank_mask:0xf bound_ctrl:1
	v_pk_mul_f32 v[48:49], v[200:201], v[48:49]
	v_fmac_f32_dpp v191, v179, v111 row_shr:1 row_mask:0xf bank_mask:0xf bound_ctrl:1
	v_rcp_f32_e32 v178, v186
	v_pk_mul_f32 v[48:49], v[206:207], v[48:49]
	v_rcp_f32_e32 v179, v187
	v_pk_mul_f32 v[186:187], v[158:159], s[82:83] op_sel_hi:[1,0]
	v_fmac_f32_dpp v170, v182, v110 row_shr:1 row_mask:0xf bank_mask:0xf bound_ctrl:1
	v_fmac_f32_dpp v171, v183, v111 row_shr:1 row_mask:0xf bank_mask:0xf bound_ctrl:1
	v_pk_mul_f32 v[154:155], v[154:155], v[178:179]
	v_exp_f32_e32 v178, v186
	v_exp_f32_e32 v179, v187
	v_pk_mul_f32 v[154:155], v[190:191], v[154:155]
	v_pk_add_f32 v[178:179], v[178:179], 1.0 op_sel_hi:[1,0]
	v_rcp_f32_e32 v182, v178
	v_rcp_f32_e32 v183, v179
	v_pk_fma_f32 v[178:179], v[192:193], v[164:165], v[168:169]
	v_pk_mul_f32 v[158:159], v[158:159], v[182:183]
	v_pk_mul_f32 v[158:159], v[170:171], v[158:159]
	v_pk_fma_f32 v[170:171], v[172:173], v[144:145], v[148:149]
	v_pk_fma_f32 v[182:183], v[144:145], v[188:189], v[148:149]
	v_fmac_f32_dpp v196, v184, v112 row_shr:1 row_mask:0xf bank_mask:0xf bound_ctrl:1
	v_pk_fma_f32 v[170:171], v[128:129], v[160:161], v[170:171]
	v_pk_fma_f32 v[182:183], v[128:129], v[172:173], v[182:183]
	v_fmac_f32_dpp v197, v185, v113 row_shr:1 row_mask:0xf bank_mask:0xf bound_ctrl:1
	v_pk_fma_f32 v[170:171], v[124:125], v[156:157], v[170:171]
	v_pk_fma_f32 v[182:183], v[124:125], v[160:161], v[182:183]
	v_fmac_f32_dpp v178, v184, v116 row_shr:1 row_mask:0xf bank_mask:0xf bound_ctrl:1
	v_pk_mul_f32 v[186:187], v[170:171], s[82:83] op_sel_hi:[1,0]
	v_pk_mul_f32 v[190:191], v[182:183], s[82:83] op_sel_hi:[1,0]
	v_fmac_f32_dpp v179, v185, v117 row_shr:1 row_mask:0xf bank_mask:0xf bound_ctrl:1
	v_exp_f32_e32 v192, v186
	v_exp_f32_e32 v193, v187
	v_exp_f32_e32 v186, v190
	v_exp_f32_e32 v187, v191
	v_fmac_f32_dpp v178, v180, v112 row_shr:1 row_mask:0xf bank_mask:0xf bound_ctrl:1
	v_fmac_f32_dpp v179, v181, v113 row_shr:1 row_mask:0xf bank_mask:0xf bound_ctrl:1
	v_pk_add_f32 v[190:191], v[192:193], 1.0 op_sel_hi:[1,0]
	v_pk_fma_f32 v[192:193], v[160:161], v[144:145], v[148:149]
	v_pk_add_f32 v[186:187], v[186:187], 1.0 op_sel_hi:[1,0]
	v_rcp_f32_e32 v194, v190
	v_rcp_f32_e32 v195, v191
	v_rcp_f32_e32 v190, v186
	v_rcp_f32_e32 v191, v187
	v_pk_fma_f32 v[186:187], v[156:157], v[144:145], v[148:149]
	v_pk_mul_f32 v[170:171], v[170:171], v[194:195]
	v_pk_fma_f32 v[192:193], v[156:157], v[128:129], v[192:193]
	v_pk_mul_f32 v[182:183], v[182:183], v[190:191]
	v_fmac_f32_dpp v186, v188, v128 row_shr:1 row_mask:0xf bank_mask:0xf bound_ctrl:1
	v_fmac_f32_dpp v192, v188, v124 row_shr:1 row_mask:0xf bank_mask:0xf bound_ctrl:1
	v_fmac_f32_dpp v193, v189, v125 row_shr:1 row_mask:0xf bank_mask:0xf bound_ctrl:1
	v_fmac_f32_dpp v187, v189, v129 row_shr:1 row_mask:0xf bank_mask:0xf bound_ctrl:1
	v_fmac_f32_dpp v186, v172, v124 row_shr:1 row_mask:0xf bank_mask:0xf bound_ctrl:1
	v_pk_mul_f32 v[190:191], v[192:193], s[82:83] op_sel_hi:[1,0]
	v_fmac_f32_dpp v187, v173, v125 row_shr:1 row_mask:0xf bank_mask:0xf bound_ctrl:1
	v_exp_f32_e32 v194, v190
	v_exp_f32_e32 v195, v191
	v_pk_mul_f32 v[190:191], v[186:187], s[82:83] op_sel_hi:[1,0]
	v_exp_f32_e32 v200, v190
	v_pk_add_f32 v[194:195], v[194:195], 1.0 op_sel_hi:[1,0]
	v_exp_f32_e32 v201, v191
	v_pk_fma_f32 v[190:191], v[102:103], v[26:27], v[30:31]
	v_rcp_f32_e32 v204, v194
	v_rcp_f32_e32 v205, v195
	v_pk_add_f32 v[194:195], v[200:201], 1.0 op_sel_hi:[1,0]
	v_pk_fma_f32 v[190:191], v[78:79], v[6:7], v[190:191]
	v_pk_mul_f32 v[192:193], v[192:193], v[204:205]
	v_rcp_f32_e32 v200, v194
	v_rcp_f32_e32 v201, v195
	v_pk_fma_f32 v[190:191], v[150:151], v[2:3], v[190:191]
	v_pk_fma_f32 v[194:195], v[78:79], v[26:27], v[30:31]
	v_pk_mul_f32 v[186:187], v[186:187], v[200:201]
	v_pk_fma_f32 v[194:195], v[150:151], v[6:7], v[194:195]
	v_pk_mul_f32 v[178:179], v[178:179], v[186:187]
	v_pk_fma_f32 v[186:187], v[138:139], v[2:3], v[194:195]
	v_pk_fma_f32 v[194:195], v[104:105], v[28:29], v[32:33]
	v_pk_fma_f32 v[200:201], v[106:107], v[18:19], v[22:23]
	v_pk_fma_f32 v[204:205], v[82:83], v[18:19], v[22:23]
	v_pk_fma_f32 v[206:207], v[66:67], v[18:19], v[22:23]
	v_pk_fma_f32 v[200:201], v[82:83], v[14:15], v[200:201]
	v_pk_fma_f32 v[204:205], v[66:67], v[14:15], v[204:205]
	v_pk_fma_f32 v[194:195], v[80:81], v[8:9], v[194:195]
	v_pk_fma_f32 v[66:67], v[66:67], v[10:11], v[200:201]
	v_pk_fma_f32 v[200:201], v[54:55], v[10:11], v[204:205]
	v_pk_fma_f32 v[204:205], v[54:55], v[14:15], v[206:207]
	v_pk_mul_f32 v[206:207], v[66:67], s[82:83] op_sel_hi:[1,0]
	v_pk_fma_f32 v[54:55], v[54:55], v[18:19], v[22:23]
	v_fmac_f32_dpp v204, v106, v10 row_shr:1 row_mask:0xf bank_mask:0xf bound_ctrl:1
	v_fmac_f32_dpp v205, v107, v11 row_shr:1 row_mask:0xf bank_mask:0xf bound_ctrl:1
	v_pk_fma_f32 v[194:195], v[152:153], v[4:5], v[194:195]
	v_fmac_f32_dpp v54, v106, v14 row_shr:1 row_mask:0xf bank_mask:0xf bound_ctrl:1
	v_fmac_f32_dpp v55, v107, v15 row_shr:1 row_mask:0xf bank_mask:0xf bound_ctrl:1
	v_exp_f32_e32 v106, v206
	v_exp_f32_e32 v107, v207
	v_pk_fma_f32 v[206:207], v[80:81], v[28:29], v[32:33]
	v_pk_mul_f32 v[182:183], v[198:199], v[182:183]
	v_pk_mul_f32 v[198:199], v[200:201], s[82:83] op_sel_hi:[1,0]
	v_pk_add_f32 v[106:107], v[106:107], 1.0 op_sel_hi:[1,0]
	v_pk_fma_f32 v[206:207], v[152:153], v[8:9], v[206:207]
	v_pk_mul_f32 v[170:171], v[202:203], v[170:171]
	v_rcp_f32_e32 v202, v106
	v_rcp_f32_e32 v203, v107
	v_exp_f32_e32 v106, v198
	v_exp_f32_e32 v107, v199
	v_pk_fma_f32 v[198:199], v[140:141], v[4:5], v[206:207]
	v_pk_mul_f32 v[66:67], v[66:67], v[202:203]
	v_pk_fma_f32 v[202:203], v[152:153], v[28:29], v[32:33]
	v_pk_add_f32 v[106:107], v[106:107], 1.0 op_sel_hi:[1,0]
	v_pk_mul_f32 v[66:67], v[190:191], v[66:67]
	v_pk_fma_f32 v[190:191], v[150:151], v[26:27], v[30:31]
	v_rcp_f32_e32 v206, v106
	v_rcp_f32_e32 v207, v107
	v_pk_mul_f32 v[106:107], v[204:205], s[82:83] op_sel_hi:[1,0]
	v_pk_fma_f32 v[190:191], v[138:139], v[6:7], v[190:191]
	v_pk_fma_f32 v[202:203], v[140:141], v[8:9], v[202:203]
	v_pk_mul_f32 v[200:201], v[200:201], v[206:207]
	v_exp_f32_e32 v206, v106
	v_exp_f32_e32 v207, v107
	v_pk_mul_f32 v[106:107], v[186:187], v[200:201]
	v_fmac_f32_dpp v190, v102, v2 row_shr:1 row_mask:0xf bank_mask:0xf bound_ctrl:1
	v_fmac_f32_dpp v191, v103, v3 row_shr:1 row_mask:0xf bank_mask:0xf bound_ctrl:1
	v_pk_mul_f32 v[186:187], v[196:197], v[192:193]
	v_pk_add_f32 v[192:193], v[206:207], 1.0 op_sel_hi:[1,0]
	v_mov_b32_e32 v0, v158
	v_fmac_f32_dpp v54, v82, v10 row_shr:1 row_mask:0xf bank_mask:0xf bound_ctrl:1
	v_fmac_f32_dpp v55, v83, v11 row_shr:1 row_mask:0xf bank_mask:0xf bound_ctrl:1
	v_rcp_f32_e32 v82, v192
	v_rcp_f32_e32 v83, v193
	v_pk_mul_f32 v[192:193], v[54:55], s[82:83] op_sel_hi:[1,0]
	v_pk_fma_f32 v[196:197], v[138:139], v[26:27], v[30:31]
	v_pk_mul_f32 v[82:83], v[204:205], v[82:83]
	v_exp_f32_e32 v200, v192
	v_exp_f32_e32 v201, v193
	v_pk_mul_f32 v[82:83], v[190:191], v[82:83]
	v_fmac_f32_dpp v196, v102, v6 row_shr:1 row_mask:0xf bank_mask:0xf bound_ctrl:1
	v_fmac_f32_dpp v197, v103, v7 row_shr:1 row_mask:0xf bank_mask:0xf bound_ctrl:1
	s_nop 0
	v_fmac_f32_dpp v196, v78, v2 row_shr:1 row_mask:0xf bank_mask:0xf bound_ctrl:1
	v_fmac_f32_dpp v197, v79, v3 row_shr:1 row_mask:0xf bank_mask:0xf bound_ctrl:1
	v_pk_add_f32 v[78:79], v[200:201], 1.0 op_sel_hi:[1,0]
	v_pk_fma_f32 v[102:103], v[84:85], v[20:21], v[24:25]
	v_rcp_f32_e32 v190, v78
	v_rcp_f32_e32 v191, v79
	v_pk_fma_f32 v[78:79], v[68:69], v[16:17], v[102:103]
	v_pk_mul_f32 v[54:55], v[54:55], v[190:191]
	v_pk_fma_f32 v[78:79], v[56:57], v[12:13], v[78:79]
	v_pk_mul_f32 v[54:55], v[196:197], v[54:55]
	v_pk_fma_f32 v[102:103], v[140:141], v[28:29], v[32:33]
	v_pk_mul_f32 v[190:191], v[78:79], s[82:83] op_sel_hi:[1,0]
	v_pk_fma_f32 v[192:193], v[108:109], v[20:21], v[24:25]
	v_fmac_f32_dpp v202, v104, v4 row_shr:1 row_mask:0xf bank_mask:0xf bound_ctrl:1
	v_exp_f32_e32 v196, v190
	v_exp_f32_e32 v197, v191
	v_pk_fma_f32 v[190:191], v[84:85], v[16:17], v[192:193]
	v_fmac_f32_dpp v203, v105, v5 row_shr:1 row_mask:0xf bank_mask:0xf bound_ctrl:1
	v_fmac_f32_dpp v102, v104, v8 row_shr:1 row_mask:0xf bank_mask:0xf bound_ctrl:1
	v_fmac_f32_dpp v103, v105, v9 row_shr:1 row_mask:0xf bank_mask:0xf bound_ctrl:1
	v_pk_fma_f32 v[190:191], v[68:69], v[12:13], v[190:191]
	v_fmac_f32_dpp v102, v80, v4 row_shr:1 row_mask:0xf bank_mask:0xf bound_ctrl:1
	v_fmac_f32_dpp v103, v81, v5 row_shr:1 row_mask:0xf bank_mask:0xf bound_ctrl:1
	v_pk_add_f32 v[192:193], v[196:197], 1.0 op_sel_hi:[1,0]
	v_pk_mul_f32 v[196:197], v[190:191], s[82:83] op_sel_hi:[1,0]
	v_pk_fma_f32 v[200:201], v[68:69], v[20:21], v[24:25]
	v_rcp_f32_e32 v204, v192
	v_exp_f32_e32 v206, v196
	v_exp_f32_e32 v207, v197
	v_rcp_f32_e32 v205, v193
	v_pk_fma_f32 v[192:193], v[56:57], v[16:17], v[200:201]
	v_pk_fma_f32 v[56:57], v[56:57], v[20:21], v[24:25]
	v_pk_add_f32 v[196:197], v[206:207], 1.0 op_sel_hi:[1,0]
	v_pk_mul_f32 v[78:79], v[78:79], v[204:205]
	v_fmac_f32_dpp v192, v108, v12 row_shr:1 row_mask:0xf bank_mask:0xf bound_ctrl:1
	v_rcp_f32_e32 v200, v196
	v_rcp_f32_e32 v201, v197
	v_pk_mul_f32 v[78:79], v[198:199], v[78:79]
	v_fmac_f32_dpp v193, v109, v13 row_shr:1 row_mask:0xf bank_mask:0xf bound_ctrl:1
	v_fmac_f32_dpp v56, v108, v16 row_shr:1 row_mask:0xf bank_mask:0xf bound_ctrl:1
	v_fmac_f32_dpp v57, v109, v17 row_shr:1 row_mask:0xf bank_mask:0xf bound_ctrl:1
	v_pk_mul_f32 v[190:191], v[190:191], v[200:201]
	v_pk_mul_f32 v[196:197], v[192:193], s[82:83] op_sel_hi:[1,0]
	v_fmac_f32_dpp v56, v84, v12 row_shr:1 row_mask:0xf bank_mask:0xf bound_ctrl:1
	v_fmac_f32_dpp v57, v85, v13 row_shr:1 row_mask:0xf bank_mask:0xf bound_ctrl:1
	v_mov_b32_e32 v158, v182
	v_exp_f32_e32 v198, v196
	v_exp_f32_e32 v199, v197
	v_pk_mul_f32 v[196:197], v[56:57], s[82:83] op_sel_hi:[1,0]
	v_mov_b32_e32 v170, v170
	v_mov_b32_e32 v182, v187
	v_mov_b32_e32 v178, v178
	v_exp_f32_e32 v200, v196
	v_pk_add_f32 v[198:199], v[198:199], 1.0 op_sel_hi:[1,0]
	v_exp_f32_e32 v201, v197
	v_rcp_f32_e32 v196, v198
	v_rcp_f32_e32 v197, v199
	v_pk_add_f32 v[198:199], v[200:201], 1.0 op_sel_hi:[1,0]
	v_mov_b32_e32 v82, v82
	v_mov_b32_e32 v55, v55
	v_pk_mul_f32 v[192:193], v[192:193], v[196:197]
	v_rcp_f32_e32 v196, v198
	v_rcp_f32_e32 v197, v199
	v_pk_mul_f32 v[190:191], v[194:195], v[190:191]
	v_mov_b32_e32 v78, v78
	v_pk_mul_f32 v[56:57], v[56:57], v[196:197]
	v_pk_mul_f32 v[56:57], v[102:103], v[56:57]
	v_pk_mul_f32 v[102:103], v[202:203], v[192:193]
	v_mbcnt_lo_u32_b32 v187, -1, s0
	v_mov_b64_e32 v[192:193], s[12:13]
	v_cvt_pk_bf16_f32 v196, v154, v155
	v_mbcnt_hi_u32_b32 v187, -1, v187
	v_cvt_pk_bf16_f32 v197, v178, v179
	v_cvt_pk_bf16_f32 v198, v54, v55
	v_and_b32_e32 v54, 15, v187
	v_ashrrev_i32_e32 v55, 1, v187
	v_cvt_pk_bf16_f32 v199, v56, v57
	v_cmp_ne_u32_e64 s[98:99], 0, v54
	s_nop 3
	v_and_b32_e32 v55, -8, v55
	v_lshl_or_b32 v54, v54, 2, s21
	v_cvt_pk_bf16_f32 v200, v0, v159
	v_add_u32_e32 v56, s19, v55
	v_mad_i64_i32 v[54:55], s[2:3], v54, s94, v[192:193]
	v_cvt_pk_bf16_f32 v201, v186, v182
	v_ashrrev_i32_e32 v57, 31, v56
	v_cvt_pk_bf16_f32 v202, v82, v83
	v_cvt_pk_bf16_f32 v203, v102, v103
	v_lshlrev_b64 v[56:57], 1, v[56:57]
	v_cvt_pk_bf16_f32 v192, v48, v49
	v_cvt_pk_bf16_f32 v193, v170, v171
	v_lshl_add_u64 v[48:49], v[54:55], 0, v[56:57]
	v_cvt_pk_bf16_f32 v194, v106, v107
	v_cvt_pk_bf16_f32 v195, v78, v79
	s_mul_i32 vcc_lo, s94, 0x1
	s_mov_b32 vcc_hi, 0
	v_lshl_add_u64 v[54:55], v[48:49], 0, vcc
	s_mov_b64 exec, s[98:99]
	global_store_dwordx4 v[48:49], v[196:199], off
	s_mov_b64 exec, -1
	s_mul_i32 vcc_lo, s94, 0x2
	s_mov_b32 vcc_hi, 0
	v_lshl_add_u64 v[56:57], v[48:49], 0, vcc
	s_mov_b64 exec, s[98:99]
	global_store_dwordx4 v[54:55], v[200:203], off
	s_mov_b64 exec, -1
	v_cvt_pk_bf16_f32 v207, v190, v191
	global_store_dwordx4 v[56:57], v[192:195], off
	v_cvt_pk_bf16_f32 v204, v46, v47
	v_cvt_pk_bf16_f32 v205, v158, v183
	v_cvt_pk_bf16_f32 v206, v66, v67
	s_mul_i32 vcc_lo, s94, 0x3
	s_mov_b32 vcc_hi, 0
	v_lshl_add_u64 v[46:47], v[48:49], 0, vcc
	global_store_dwordx4 v[46:47], v[204:207], off
	v_pk_fma_f32 v[54:55], v[142:143], v[98:99], v[146:147]
	v_pk_fma_f32 v[56:57], v[144:145], v[100:101], v[148:149]
	v_pk_fma_f32 v[66:67], v[162:163], v[90:91], v[166:167]
	v_pk_fma_f32 v[46:47], v[126:127], v[94:95], v[54:55]
	v_pk_fma_f32 v[54:55], v[128:129], v[96:97], v[56:57]
	v_pk_fma_f32 v[56:57], v[114:115], v[86:87], v[66:67]
	v_pk_fma_f32 v[46:47], v[122:123], v[118:119], v[46:47]
	v_pk_fma_f32 v[54:55], v[124:125], v[120:121], v[54:55]
	v_pk_fma_f32 v[56:57], v[110:111], v[174:175], v[56:57]
	v_pk_mul_f32 v[66:67], v[46:47], s[82:83] op_sel_hi:[1,0]
	v_pk_fma_f32 v[78:79], v[144:145], v[96:97], v[148:149]
	v_pk_fma_f32 v[82:83], v[142:143], v[94:95], v[146:147]
	v_exp_f32_e32 v102, v66
	v_exp_f32_e32 v103, v67
	v_pk_fma_f32 v[66:67], v[128:129], v[120:121], v[78:79]
	v_pk_fma_f32 v[78:79], v[126:127], v[118:119], v[82:83]
	v_pk_fma_f32 v[82:83], v[164:165], v[88:89], v[168:169]
	v_pk_add_f32 v[102:103], v[102:103], 1.0 op_sel_hi:[1,0]
	v_pk_fma_f32 v[66:67], v[124:125], v[136:137], v[66:67]
	v_pk_fma_f32 v[78:79], v[122:123], v[134:135], v[78:79]
	v_rcp_f32_e32 v106, v102
	v_rcp_f32_e32 v107, v103
	v_pk_mul_f32 v[102:103], v[78:79], s[82:83] op_sel_hi:[1,0]
	v_pk_fma_f32 v[82:83], v[116:117], v[176:177], v[82:83]
	v_pk_fma_f32 v[154:155], v[162:163], v[86:87], v[166:167]
	v_pk_mul_f32 v[46:47], v[46:47], v[106:107]
	v_exp_f32_e32 v106, v102
	v_exp_f32_e32 v107, v103
	v_pk_mul_f32 v[46:47], v[56:57], v[46:47]
	v_pk_fma_f32 v[56:57], v[112:113], v[132:133], v[82:83]
	v_pk_fma_f32 v[82:83], v[114:115], v[174:175], v[154:155]
	v_pk_add_f32 v[102:103], v[106:107], 1.0 op_sel_hi:[1,0]
	v_pk_fma_f32 v[106:107], v[142:143], v[118:119], v[146:147]
	v_pk_fma_f32 v[82:83], v[110:111], v[130:131], v[82:83]
	v_rcp_f32_e32 v118, v102
	v_rcp_f32_e32 v119, v103
	v_pk_fma_f32 v[102:103], v[126:127], v[134:135], v[106:107]
	v_pk_fma_f32 v[106:107], v[144:145], v[120:121], v[148:149]
	v_pk_fma_f32 v[120:121], v[164:165], v[176:177], v[168:169]
	v_pk_mul_f32 v[78:79], v[78:79], v[118:119]
	v_fmac_f32_dpp v102, v98, v122 row_shr:1 row_mask:0xf bank_mask:0xf bound_ctrl:1
	v_fmac_f32_dpp v103, v99, v123 row_shr:1 row_mask:0xf bank_mask:0xf bound_ctrl:1
	v_pk_fma_f32 v[106:107], v[128:129], v[136:137], v[106:107]
	v_pk_mul_f32 v[78:79], v[82:83], v[78:79]
	v_pk_mul_f32 v[82:83], v[102:103], s[82:83] op_sel_hi:[1,0]
	v_pk_fma_f32 v[118:119], v[162:163], v[174:175], v[166:167]
	v_pk_fma_f32 v[120:121], v[116:117], v[132:133], v[120:121]
	v_exp_f32_e32 v154, v82
	v_exp_f32_e32 v155, v83
	v_pk_fma_f32 v[82:83], v[114:115], v[130:131], v[118:119]
	v_pk_fma_f32 v[118:119], v[162:163], v[130:131], v[166:167]
	v_pk_fma_f32 v[130:131], v[142:143], v[134:135], v[146:147]
	v_pk_add_f32 v[134:135], v[154:155], 1.0 op_sel_hi:[1,0]
	v_fmac_f32_dpp v82, v90, v110 row_shr:1 row_mask:0xf bank_mask:0xf bound_ctrl:1
	v_fmac_f32_dpp v83, v91, v111 row_shr:1 row_mask:0xf bank_mask:0xf bound_ctrl:1
	v_fmac_f32_dpp v118, v90, v114 row_shr:1 row_mask:0xf bank_mask:0xf bound_ctrl:1
	v_rcp_f32_e32 v142, v134
	v_rcp_f32_e32 v143, v135
	v_fmac_f32_dpp v119, v91, v115 row_shr:1 row_mask:0xf bank_mask:0xf bound_ctrl:1
	v_fmac_f32_dpp v118, v86, v110 row_shr:1 row_mask:0xf bank_mask:0xf bound_ctrl:1
	v_fmac_f32_dpp v130, v98, v126 row_shr:1 row_mask:0xf bank_mask:0xf bound_ctrl:1
	v_fmac_f32_dpp v119, v87, v111 row_shr:1 row_mask:0xf bank_mask:0xf bound_ctrl:1
	v_fmac_f32_dpp v131, v99, v127 row_shr:1 row_mask:0xf bank_mask:0xf bound_ctrl:1
	v_pk_mul_f32 v[86:87], v[102:103], v[142:143]
	v_pk_fma_f32 v[90:91], v[164:165], v[132:133], v[168:169]
	v_fmac_f32_dpp v130, v94, v122 row_shr:1 row_mask:0xf bank_mask:0xf bound_ctrl:1
	v_pk_mul_f32 v[82:83], v[82:83], v[86:87]
	v_fmac_f32_dpp v131, v95, v123 row_shr:1 row_mask:0xf bank_mask:0xf bound_ctrl:1
	v_pk_fma_f32 v[86:87], v[144:145], v[136:137], v[148:149]
	v_pk_mul_f32 v[94:95], v[130:131], s[82:83] op_sel_hi:[1,0]
	v_pk_fma_f32 v[98:99], v[164:165], v[92:93], v[168:169]
	v_exp_f32_e32 v102, v94
	v_exp_f32_e32 v103, v95
	v_fmac_f32_dpp v106, v100, v124 row_shr:1 row_mask:0xf bank_mask:0xf bound_ctrl:1
	v_fmac_f32_dpp v107, v101, v125 row_shr:1 row_mask:0xf bank_mask:0xf bound_ctrl:1
	v_pk_add_f32 v[94:95], v[102:103], 1.0 op_sel_hi:[1,0]
	v_pk_fma_f32 v[98:99], v[116:117], v[88:89], v[98:99]
	v_rcp_f32_e32 v102, v94
	v_rcp_f32_e32 v103, v95
	s_nop 0
	v_pk_mul_f32 v[94:95], v[130:131], v[102:103]
	v_fmac_f32_dpp v86, v100, v128 row_shr:1 row_mask:0xf bank_mask:0xf bound_ctrl:1
	v_fmac_f32_dpp v87, v101, v129 row_shr:1 row_mask:0xf bank_mask:0xf bound_ctrl:1
	v_pk_mul_f32 v[94:95], v[118:119], v[94:95]
	v_fmac_f32_dpp v86, v96, v124 row_shr:1 row_mask:0xf bank_mask:0xf bound_ctrl:1
	v_fmac_f32_dpp v87, v97, v125 row_shr:1 row_mask:0xf bank_mask:0xf bound_ctrl:1
	v_pk_fma_f32 v[96:97], v[112:113], v[176:177], v[98:99]
	v_pk_mul_f32 v[98:99], v[86:87], s[82:83] op_sel_hi:[1,0]
	v_pk_mul_f32 v[100:101], v[54:55], s[82:83] op_sel_hi:[1,0]
	v_fmac_f32_dpp v90, v92, v116 row_shr:1 row_mask:0xf bank_mask:0xf bound_ctrl:1
	v_exp_f32_e32 v102, v98
	v_exp_f32_e32 v103, v99
	v_exp_f32_e32 v98, v100
	v_exp_f32_e32 v99, v101
	v_fmac_f32_dpp v91, v93, v117 row_shr:1 row_mask:0xf bank_mask:0xf bound_ctrl:1
	v_fmac_f32_dpp v120, v92, v112 row_shr:1 row_mask:0xf bank_mask:0xf bound_ctrl:1
	v_fmac_f32_dpp v121, v93, v113 row_shr:1 row_mask:0xf bank_mask:0xf bound_ctrl:1
	v_fmac_f32_dpp v90, v88, v112 row_shr:1 row_mask:0xf bank_mask:0xf bound_ctrl:1
	v_fmac_f32_dpp v91, v89, v113 row_shr:1 row_mask:0xf bank_mask:0xf bound_ctrl:1
	v_pk_add_f32 v[88:89], v[98:99], 1.0 op_sel_hi:[1,0]
	v_pk_mul_f32 v[92:93], v[66:67], s[82:83] op_sel_hi:[1,0]
	v_pk_mul_f32 v[98:99], v[106:107], s[82:83] op_sel_hi:[1,0]
	v_rcp_f32_e32 v100, v88
	v_rcp_f32_e32 v101, v89
	v_exp_f32_e32 v88, v92
	v_exp_f32_e32 v89, v93
	v_exp_f32_e32 v92, v98
	v_pk_mul_f32 v[54:55], v[54:55], v[100:101]
	v_exp_f32_e32 v93, v99
	v_pk_add_f32 v[88:89], v[88:89], 1.0 op_sel_hi:[1,0]
	v_pk_fma_f32 v[98:99], v[36:37], v[28:29], v[32:33]
	v_pk_add_f32 v[100:101], v[102:103], 1.0 op_sel_hi:[1,0]
	v_pk_add_f32 v[92:93], v[92:93], 1.0 op_sel_hi:[1,0]
	v_pk_fma_f32 v[98:99], v[40:41], v[8:9], v[98:99]
	v_rcp_f32_e32 v102, v100
	v_rcp_f32_e32 v110, v92
	v_rcp_f32_e32 v111, v93
	v_rcp_f32_e32 v103, v101
	v_pk_mul_f32 v[92:93], v[106:107], v[110:111]
	v_pk_mul_f32 v[86:87], v[86:87], v[102:103]
	v_rcp_f32_e32 v100, v88
	v_rcp_f32_e32 v101, v89
	v_pk_mul_f32 v[86:87], v[90:91], v[86:87]
	v_mov_b32_e32 v0, v78
	v_pk_fma_f32 v[88:89], v[34:35], v[26:27], v[30:31]
	v_pk_mul_f32 v[66:67], v[66:67], v[100:101]
	v_pk_fma_f32 v[90:91], v[42:43], v[18:19], v[22:23]
	v_pk_fma_f32 v[88:89], v[38:39], v[6:7], v[88:89]
	v_pk_fma_f32 v[100:101], v[38:39], v[26:27], v[30:31]
	v_pk_fma_f32 v[90:91], v[58:59], v[14:15], v[90:91]
	v_pk_fma_f32 v[88:89], v[74:75], v[2:3], v[88:89]
	v_pk_fma_f32 v[100:101], v[74:75], v[6:7], v[100:101]
	v_pk_fma_f32 v[90:91], v[50:51], v[10:11], v[90:91]
	v_pk_fma_f32 v[74:75], v[74:75], v[26:27], v[30:31]
	v_pk_fma_f32 v[100:101], v[62:63], v[2:3], v[100:101]
	v_pk_mul_f32 v[102:103], v[90:91], s[82:83] op_sel_hi:[1,0]
	v_pk_fma_f32 v[26:27], v[62:63], v[26:27], v[30:31]
	v_pk_fma_f32 v[30:31], v[62:63], v[6:7], v[74:75]
	v_exp_f32_e32 v62, v102
	v_exp_f32_e32 v63, v103
	v_fmac_f32_dpp v26, v34, v6 row_shr:1 row_mask:0xf bank_mask:0xf bound_ctrl:1
	v_fmac_f32_dpp v27, v35, v7 row_shr:1 row_mask:0xf bank_mask:0xf bound_ctrl:1
	v_fmac_f32_dpp v30, v34, v2 row_shr:1 row_mask:0xf bank_mask:0xf bound_ctrl:1
	v_fmac_f32_dpp v31, v35, v3 row_shr:1 row_mask:0xf bank_mask:0xf bound_ctrl:1
	v_fmac_f32_dpp v26, v38, v2 row_shr:1 row_mask:0xf bank_mask:0xf bound_ctrl:1
	v_pk_add_f32 v[6:7], v[62:63], 1.0 op_sel_hi:[1,0]
	v_fmac_f32_dpp v27, v39, v3 row_shr:1 row_mask:0xf bank_mask:0xf bound_ctrl:1
	v_pk_fma_f32 v[2:3], v[58:59], v[18:19], v[22:23]
	v_rcp_f32_e32 v34, v6
	v_rcp_f32_e32 v35, v7
	v_pk_fma_f32 v[6:7], v[76:77], v[4:5], v[98:99]
	v_pk_fma_f32 v[2:3], v[50:51], v[14:15], v[2:3]
	v_pk_fma_f32 v[38:39], v[40:41], v[28:29], v[32:33]
	v_pk_mul_f32 v[34:35], v[90:91], v[34:35]
	v_pk_fma_f32 v[2:3], v[70:71], v[10:11], v[2:3]
	v_pk_fma_f32 v[38:39], v[76:77], v[8:9], v[38:39]
	v_pk_mul_f32 v[34:35], v[88:89], v[34:35]
	v_pk_mul_f32 v[62:63], v[2:3], s[82:83] op_sel_hi:[1,0]
	v_pk_fma_f32 v[74:75], v[76:77], v[28:29], v[32:33]
	v_pk_fma_f32 v[38:39], v[64:65], v[4:5], v[38:39]
	v_exp_f32_e32 v76, v62
	v_exp_f32_e32 v77, v63
	v_pk_fma_f32 v[50:51], v[50:51], v[18:19], v[22:23]
	v_pk_fma_f32 v[18:19], v[70:71], v[18:19], v[22:23]
	v_pk_fma_f32 v[22:23], v[64:65], v[28:29], v[32:33]
	v_pk_add_f32 v[28:29], v[76:77], 1.0 op_sel_hi:[1,0]
	v_pk_fma_f32 v[32:33], v[70:71], v[14:15], v[50:51]
	v_fmac_f32_dpp v18, v42, v14 row_shr:1 row_mask:0xf bank_mask:0xf bound_ctrl:1
	v_rcp_f32_e32 v50, v28
	v_rcp_f32_e32 v51, v29
	v_fmac_f32_dpp v19, v43, v15 row_shr:1 row_mask:0xf bank_mask:0xf bound_ctrl:1
	v_fmac_f32_dpp v32, v42, v10 row_shr:1 row_mask:0xf bank_mask:0xf bound_ctrl:1
	v_fmac_f32_dpp v33, v43, v11 row_shr:1 row_mask:0xf bank_mask:0xf bound_ctrl:1
	v_fmac_f32_dpp v18, v58, v10 row_shr:1 row_mask:0xf bank_mask:0xf bound_ctrl:1
	v_fmac_f32_dpp v19, v59, v11 row_shr:1 row_mask:0xf bank_mask:0xf bound_ctrl:1
	v_pk_mul_f32 v[2:3], v[2:3], v[50:51]
	v_pk_mul_f32 v[10:11], v[18:19], s[82:83] op_sel_hi:[1,0]
	v_pk_mul_f32 v[14:15], v[32:33], s[82:83] op_sel_hi:[1,0]
	v_pk_mul_f32 v[2:3], v[100:101], v[2:3]
	v_exp_f32_e32 v28, v10
	v_exp_f32_e32 v29, v11
	v_exp_f32_e32 v10, v14
	v_exp_f32_e32 v11, v15
	v_pk_fma_f32 v[14:15], v[64:65], v[8:9], v[74:75]
	v_pk_add_f32 v[28:29], v[28:29], 1.0 op_sel_hi:[1,0]
	v_fmac_f32_dpp v22, v36, v8 row_shr:1 row_mask:0xf bank_mask:0xf bound_ctrl:1
	v_pk_add_f32 v[10:11], v[10:11], 1.0 op_sel_hi:[1,0]
	v_rcp_f32_e32 v42, v28
	v_rcp_f32_e32 v43, v29
	v_rcp_f32_e32 v28, v10
	v_rcp_f32_e32 v29, v11
	v_fmac_f32_dpp v23, v37, v9 row_shr:1 row_mask:0xf bank_mask:0xf bound_ctrl:1
	v_pk_mul_f32 v[8:9], v[18:19], v[42:43]
	v_fmac_f32_dpp v14, v36, v4 row_shr:1 row_mask:0xf bank_mask:0xf bound_ctrl:1
	v_fmac_f32_dpp v15, v37, v5 row_shr:1 row_mask:0xf bank_mask:0xf bound_ctrl:1
	v_pk_mul_f32 v[10:11], v[32:33], v[28:29]
	v_pk_mul_f32 v[8:9], v[26:27], v[8:9]
	v_fmac_f32_dpp v22, v40, v4 row_shr:1 row_mask:0xf bank_mask:0xf bound_ctrl:1
	v_fmac_f32_dpp v23, v41, v5 row_shr:1 row_mask:0xf bank_mask:0xf bound_ctrl:1
	v_pk_mul_f32 v[4:5], v[30:31], v[10:11]
	v_mov_b32_e32 v78, v82
	v_mov_b32_e32 v82, v95
	v_pk_fma_f32 v[10:11], v[44:45], v[20:21], v[24:25]
	v_pk_fma_f32 v[18:19], v[60:61], v[20:21], v[24:25]
	v_pk_mul_f32 v[26:27], v[96:97], v[54:55]
	v_pk_fma_f32 v[10:11], v[60:61], v[16:17], v[10:11]
	v_pk_fma_f32 v[18:19], v[52:53], v[16:17], v[18:19]
	v_pk_mul_f32 v[28:29], v[56:57], v[66:67]
	v_pk_fma_f32 v[10:11], v[52:53], v[12:13], v[10:11]
	v_pk_fma_f32 v[18:19], v[72:73], v[12:13], v[18:19]
	v_pk_mul_f32 v[30:31], v[120:121], v[92:93]
	v_pk_mul_f32 v[32:33], v[10:11], s[82:83] op_sel_hi:[1,0]
	v_pk_mul_f32 v[36:37], v[18:19], s[82:83] op_sel_hi:[1,0]
	v_mov_b32_e32 v4, v4
	v_exp_f32_e32 v40, v32
	v_exp_f32_e32 v41, v33
	v_exp_f32_e32 v32, v36
	v_exp_f32_e32 v33, v37
	v_pk_fma_f32 v[36:37], v[52:53], v[20:21], v[24:25]
	v_pk_add_f32 v[40:41], v[40:41], 1.0 op_sel_hi:[1,0]
	v_pk_fma_f32 v[20:21], v[72:73], v[20:21], v[24:25]
	v_pk_add_f32 v[24:25], v[32:33], 1.0 op_sel_hi:[1,0]
	v_rcp_f32_e32 v32, v40
	v_rcp_f32_e32 v33, v41
	v_rcp_f32_e32 v40, v24
	v_rcp_f32_e32 v41, v25
	v_pk_fma_f32 v[24:25], v[72:73], v[16:17], v[36:37]
	v_pk_mul_f32 v[10:11], v[10:11], v[32:33]
	v_fmac_f32_dpp v20, v44, v16 row_shr:1 row_mask:0xf bank_mask:0xf bound_ctrl:1
	v_pk_mul_f32 v[18:19], v[18:19], v[40:41]
	v_pk_mul_f32 v[6:7], v[6:7], v[10:11]
	v_fmac_f32_dpp v21, v45, v17 row_shr:1 row_mask:0xf bank_mask:0xf bound_ctrl:1
	v_fmac_f32_dpp v24, v44, v12 row_shr:1 row_mask:0xf bank_mask:0xf bound_ctrl:1
	v_fmac_f32_dpp v25, v45, v13 row_shr:1 row_mask:0xf bank_mask:0xf bound_ctrl:1
	v_fmac_f32_dpp v20, v60, v12 row_shr:1 row_mask:0xf bank_mask:0xf bound_ctrl:1
	v_fmac_f32_dpp v21, v61, v13 row_shr:1 row_mask:0xf bank_mask:0xf bound_ctrl:1
	v_pk_mul_f32 v[10:11], v[24:25], s[82:83] op_sel_hi:[1,0]
	v_pk_mul_f32 v[12:13], v[20:21], s[82:83] op_sel_hi:[1,0]
	v_pk_mul_f32 v[16:17], v[38:39], v[18:19]
	v_exp_f32_e32 v18, v10
	v_exp_f32_e32 v32, v12
	v_exp_f32_e32 v33, v13
	v_exp_f32_e32 v19, v11
	v_mov_b32_e32 v6, v6
	v_mov_b32_e32 v17, v17
	v_pk_add_f32 v[10:11], v[32:33], 1.0 op_sel_hi:[1,0]
	v_pk_add_f32 v[12:13], v[18:19], 1.0 op_sel_hi:[1,0]
	v_rcp_f32_e32 v18, v10
	v_rcp_f32_e32 v19, v11
	v_rcp_f32_e32 v10, v12
	v_rcp_f32_e32 v11, v13
	v_pk_mul_f32 v[12:13], v[20:21], v[18:19]
	v_pk_mul_f32 v[10:11], v[24:25], v[10:11]
	v_pk_mul_f32 v[12:13], v[22:23], v[12:13]
	v_pk_mul_f32 v[10:11], v[14:15], v[10:11]
	v_mov_b32_e32 v12, v12
	v_cvt_pk_bf16_f32 v22, v8, v9
	v_cvt_pk_bf16_f32 v20, v94, v82
	v_cvt_pk_bf16_f32 v21, v86, v87
	v_cvt_pk_bf16_f32 v23, v12, v13
	s_mul_i32 vcc_lo, s94, 0x80
	s_mov_b32 vcc_hi, 0
	v_lshl_add_u64 v[8:9], v[48:49], 0, vcc
	v_cvt_pk_bf16_f32 v12, v78, v83
	v_cvt_pk_bf16_f32 v13, v30, v31
	v_cvt_pk_bf16_f32 v14, v4, v5
	v_cvt_pk_bf16_f32 v15, v10, v11
	s_mul_i32 vcc_lo, s94, 0x81
	s_mov_b32 vcc_hi, 0
	v_lshl_add_u64 v[4:5], v[48:49], 0, vcc
	s_mov_b64 exec, s[98:99]
	global_store_dwordx4 v[8:9], v[20:23], off
	s_mov_b64 exec, -1
	v_cvt_pk_bf16_f32 v36, v0, v79
	s_mov_b64 exec, s[98:99]
	global_store_dwordx4 v[4:5], v[12:15], off
	s_mov_b64 exec, -1
	v_cvt_pk_bf16_f32 v37, v28, v29
	v_cvt_pk_bf16_f32 v38, v2, v3
	v_cvt_pk_bf16_f32 v39, v16, v17
	s_mul_i32 vcc_lo, s94, 0x82
	s_mov_b32 vcc_hi, 0
	v_lshl_add_u64 v[2:3], v[48:49], 0, vcc
	v_cvt_pk_bf16_f32 v8, v46, v47
	v_cvt_pk_bf16_f32 v9, v26, v27
	global_store_dwordx4 v[2:3], v[36:39], off
	v_cvt_pk_bf16_f32 v10, v34, v35
	v_cvt_pk_bf16_f32 v11, v6, v7
	s_mul_i32 vcc_lo, s94, 0x83
	s_mov_b32 vcc_hi, 0
	v_lshl_add_u64 v[4:5], v[48:49], 0, vcc
	global_store_dwordx4 v[4:5], v[8:11], off
	s_andn2_b64 vcc, exec, s[4:5]
	s_mov_b64 s[0:1], -1
	s_cbranch_vccnz .LBB0_694
	s_andn2_b64 vcc, exec, s[8:9]
	s_cbranch_vccnz .LBB0_693
	s_barrier
	s_branch .LBB0_693
